# ph1 gemm_in main loop rewritten: LDS-DMA (global_load_lds) 2-stage, software-pipelined frag reads
# speedup vs baseline: 1.0347x; 1.0347x over previous
.LBB0_398:
	v_mov_b64_e32 v[2:3], s[80:81]
	s_mov_b32 s4, 0x44000
	v_mad_u64_u32 v[4:5], s[0:1], v136, s4, v[2:3]
	v_mov_b64_e32 v[2:3], s[46:47]
	v_mad_i64_i32 v[6:7], s[0:1], v135, s4, v[2:3]
	v_mov_b32_e32 v2, v163
	s_mov_b32 s4, 0x22000
	v_ashrrev_i32_e32 v3, 3, v2
	v_lshlrev_b32_e32 v0, 4, v2
	v_mad_i64_i32 v[4:5], s[0:1], v3, s43, v[4:5]
	v_and_b32_e32 v0, 0x70, v0
	v_lshl_add_u64 v[130:131], v[4:5], 0, v[0:1]
	v_mad_i64_i32 v[4:5], s[0:1], v3, s43, v[6:7]
	v_lshl_add_u64 v[132:133], v[4:5], 0, v[0:1]
	v_and_b32_e32 v58, 7, v163
	v_bfe_u32 v59, v163, 4, 3
	v_xor_b32_e32 v59, v59, v58
	v_sub_u32_e32 v59, v59, v58
	v_lshlrev_b32_e32 v59, 4, v59
	v_lshrrev_b32_e32 v60, 6, v163
	v_lshlrev_b32_e32 v60, 10, v60
	v_readfirstlane_b32 s0, v130
	v_readfirstlane_b32 s1, v131
	v_readfirstlane_b32 s4, v132
	v_readfirstlane_b32 s5, v133
	v_readfirstlane_b32 s8, v60
	s_nop 3
	v_subrev_u32_e32 v50, s0, v130
	v_subrev_u32_e32 v54, s4, v132
	v_add_u32_e32 v50, v50, v59
	v_add_u32_e32 v54, v54, v59
	v_add_u32_e32 v51, 0x11000, v50
	v_add_u32_e32 v55, 0x11000, v54
	v_add_u32_e32 v52, 0x22000, v50
	v_add_u32_e32 v56, 0x22000, v54
	v_add_u32_e32 v53, 0x33000, v50
	v_add_u32_e32 v57, 0x33000, v54
	v_lshlrev_b32_e32 v58, 3, v163
	v_lshlrev_b32_e32 v59, 7, v163
	v_and_b32_e32 v60, 0x2000, v59
	v_and_b32_e32 v59, 0x780, v59
	v_and_b32_e32 v139, 64, v58
	v_xor_b32_e32 v58, v58, v163
	v_and_b32_e32 v58, 48, v58
	v_or3_b32 v58, v59, v139, v58
	v_lshlrev_b32_e32 v59, 6, v163
	v_and_b32_e32 v59, 0xffffe000, v59
	v_or_b32_e32 v137, v58, v60
	v_or_b32_e32 v138, v58, v59
	v_xor_b32_e32 v139, 64, v138
	v_xor_b32_e32 v140, 64, v137
	s_mov_b32 m0, s8
	s_nop 0
	global_load_lds_dwordx4 v50, s[0:1]
	s_add_u32 m0, s8, 0x1000
	s_nop 0
	global_load_lds_dwordx4 v51, s[0:1]
	s_add_u32 m0, s8, 0x2000
	s_nop 0
	global_load_lds_dwordx4 v52, s[0:1]
	s_add_u32 m0, s8, 0x3000
	s_nop 0
	global_load_lds_dwordx4 v53, s[0:1]
	s_add_u32 m0, s8, 0x4000
	s_nop 0
	global_load_lds_dwordx4 v54, s[4:5]
	s_add_u32 m0, s8, 0x5000
	s_nop 0
	global_load_lds_dwordx4 v55, s[4:5]
	s_add_u32 m0, s8, 0x6000
	s_nop 0
	global_load_lds_dwordx4 v56, s[4:5]
	s_add_u32 m0, s8, 0x7000
	s_nop 0
	global_load_lds_dwordx4 v57, s[4:5]
	s_add_u32 s0, s0, 0x80
	s_addc_u32 s1, s1, 0
	s_add_u32 s4, s4, 0x80
	s_addc_u32 s5, s5, 0
	s_waitcnt vmcnt(0)
	s_barrier
	s_add_u32 m0, s8, 0x8000
	ds_read_b128 v[142:145], v138
	ds_read_b128 v[158:161], v137 offset:16384
	s_nop 0
	global_load_lds_dwordx4 v50, s[0:1]
	s_add_u32 m0, s8, 0x9000
	ds_read_b128 v[182:185], v137 offset:18432
	ds_read_b128 v[186:189], v137 offset:20480
	s_nop 0
	global_load_lds_dwordx4 v51, s[0:1]
	s_add_u32 m0, s8, 0xa000
	ds_read_b128 v[206:209], v137 offset:22528
	ds_read_b128 v[146:149], v138 offset:2048
	s_nop 0
	global_load_lds_dwordx4 v52, s[0:1]
	s_add_u32 m0, s8, 0xb000
	ds_read_b128 v[150:153], v138 offset:4096
	ds_read_b128 v[154:157], v138 offset:6144
	s_nop 0
	global_load_lds_dwordx4 v53, s[0:1]
	s_add_u32 m0, s8, 0xc000
	s_nop 0
	global_load_lds_dwordx4 v54, s[4:5]
	s_add_u32 m0, s8, 0xd000
	s_nop 0
	global_load_lds_dwordx4 v55, s[4:5]
	s_add_u32 m0, s8, 0xe000
	s_nop 0
	global_load_lds_dwordx4 v56, s[4:5]
	s_add_u32 m0, s8, 0xf000
	s_nop 0
	global_load_lds_dwordx4 v57, s[4:5]
	s_add_u32 s0, s0, 0x80
	s_addc_u32 s1, s1, 0
	s_add_u32 s4, s4, 0x80
	s_addc_u32 s5, s5, 0
	s_waitcnt lgkmcnt(0)
	v_mfma_f32_16x16x32_bf16 v[94:97], v[158:161], v[142:145], 0
	ds_read_b128 v[98:101], v139
	ds_read_b128 v[114:117], v140 offset:16384
	v_mfma_f32_16x16x32_bf16 v[90:93], v[182:185], v[142:145], 0
	v_mfma_f32_16x16x32_bf16 v[86:89], v[186:189], v[142:145], 0
	ds_read_b128 v[118:121], v140 offset:18432
	ds_read_b128 v[122:125], v140 offset:20480
	v_mfma_f32_16x16x32_bf16 v[74:77], v[206:209], v[142:145], 0
	v_mfma_f32_16x16x32_bf16 v[46:49], v[158:161], v[146:149], 0
	ds_read_b128 v[126:129], v140 offset:22528
	ds_read_b128 v[102:105], v139 offset:2048
	v_mfma_f32_16x16x32_bf16 v[42:45], v[182:185], v[146:149], 0
	v_mfma_f32_16x16x32_bf16 v[38:41], v[186:189], v[146:149], 0
	ds_read_b128 v[106:109], v139 offset:4096
	ds_read_b128 v[110:113], v139 offset:6144
	v_mfma_f32_16x16x32_bf16 v[34:37], v[206:209], v[146:149], 0
	v_mfma_f32_16x16x32_bf16 v[30:33], v[158:161], v[150:153], 0
	v_mfma_f32_16x16x32_bf16 v[26:29], v[182:185], v[150:153], 0
	v_mfma_f32_16x16x32_bf16 v[22:25], v[186:189], v[150:153], 0
	v_mfma_f32_16x16x32_bf16 v[18:21], v[206:209], v[150:153], 0
	v_mfma_f32_16x16x32_bf16 v[14:17], v[158:161], v[154:157], 0
	v_mfma_f32_16x16x32_bf16 v[10:13], v[182:185], v[154:157], 0
	v_mfma_f32_16x16x32_bf16 v[2:5], v[186:189], v[154:157], 0
	v_mfma_f32_16x16x32_bf16 v[6:9], v[206:209], v[154:157], 0
	s_waitcnt vmcnt(0) lgkmcnt(0)
	s_barrier
	s_movk_i32 s9, 7
.Lg1_loop:
	v_mfma_f32_16x16x32_bf16 v[94:97], v[114:117], v[98:101], v[94:97]
	s_mov_b32 m0, s8
	ds_read_b128 v[142:145], v138 offset:32768
	ds_read_b128 v[158:161], v137 offset:49152
	v_mfma_f32_16x16x32_bf16 v[90:93], v[118:121], v[98:101], v[90:93]
	global_load_lds_dwordx4 v50, s[0:1]
	v_mfma_f32_16x16x32_bf16 v[86:89], v[122:125], v[98:101], v[86:89]
	s_add_u32 m0, s8, 0x1000
	ds_read_b128 v[182:185], v137 offset:51200
	ds_read_b128 v[186:189], v137 offset:53248
	v_mfma_f32_16x16x32_bf16 v[74:77], v[126:129], v[98:101], v[74:77]
	global_load_lds_dwordx4 v51, s[0:1]
	v_mfma_f32_16x16x32_bf16 v[46:49], v[114:117], v[102:105], v[46:49]
	s_add_u32 m0, s8, 0x2000
	ds_read_b128 v[206:209], v137 offset:55296
	ds_read_b128 v[146:149], v138 offset:34816
	v_mfma_f32_16x16x32_bf16 v[42:45], v[118:121], v[102:105], v[42:45]
	global_load_lds_dwordx4 v52, s[0:1]
	v_mfma_f32_16x16x32_bf16 v[38:41], v[122:125], v[102:105], v[38:41]
	s_add_u32 m0, s8, 0x3000
	ds_read_b128 v[150:153], v138 offset:36864
	ds_read_b128 v[154:157], v138 offset:38912
	v_mfma_f32_16x16x32_bf16 v[34:37], v[126:129], v[102:105], v[34:37]
	global_load_lds_dwordx4 v53, s[0:1]
	v_mfma_f32_16x16x32_bf16 v[30:33], v[114:117], v[106:109], v[30:33]
	s_add_u32 m0, s8, 0x4000
	v_mfma_f32_16x16x32_bf16 v[26:29], v[118:121], v[106:109], v[26:29]
	global_load_lds_dwordx4 v54, s[4:5]
	v_mfma_f32_16x16x32_bf16 v[22:25], v[122:125], v[106:109], v[22:25]
	s_add_u32 m0, s8, 0x5000
	v_mfma_f32_16x16x32_bf16 v[18:21], v[126:129], v[106:109], v[18:21]
	global_load_lds_dwordx4 v55, s[4:5]
	v_mfma_f32_16x16x32_bf16 v[14:17], v[114:117], v[110:113], v[14:17]
	s_add_u32 m0, s8, 0x6000
	v_mfma_f32_16x16x32_bf16 v[10:13], v[118:121], v[110:113], v[10:13]
	global_load_lds_dwordx4 v56, s[4:5]
	v_mfma_f32_16x16x32_bf16 v[2:5], v[122:125], v[110:113], v[2:5]
	s_add_u32 m0, s8, 0x7000
	v_mfma_f32_16x16x32_bf16 v[6:9], v[126:129], v[110:113], v[6:9]
	global_load_lds_dwordx4 v57, s[4:5]
	s_add_u32 s0, s0, 0x80
	s_addc_u32 s1, s1, 0
	s_add_u32 s4, s4, 0x80
	s_addc_u32 s5, s5, 0
	s_waitcnt lgkmcnt(0)
	v_mfma_f32_16x16x32_bf16 v[94:97], v[158:161], v[142:145], v[94:97]
	ds_read_b128 v[98:101], v139 offset:32768
	ds_read_b128 v[114:117], v140 offset:49152
	v_mfma_f32_16x16x32_bf16 v[90:93], v[182:185], v[142:145], v[90:93]
	v_mfma_f32_16x16x32_bf16 v[86:89], v[186:189], v[142:145], v[86:89]
	ds_read_b128 v[118:121], v140 offset:51200
	ds_read_b128 v[122:125], v140 offset:53248
	v_mfma_f32_16x16x32_bf16 v[74:77], v[206:209], v[142:145], v[74:77]
	v_mfma_f32_16x16x32_bf16 v[46:49], v[158:161], v[146:149], v[46:49]
	ds_read_b128 v[126:129], v140 offset:55296
	ds_read_b128 v[102:105], v139 offset:34816
	v_mfma_f32_16x16x32_bf16 v[42:45], v[182:185], v[146:149], v[42:45]
	v_mfma_f32_16x16x32_bf16 v[38:41], v[186:189], v[146:149], v[38:41]
	ds_read_b128 v[106:109], v139 offset:36864
	ds_read_b128 v[110:113], v139 offset:38912
	v_mfma_f32_16x16x32_bf16 v[34:37], v[206:209], v[146:149], v[34:37]
	v_mfma_f32_16x16x32_bf16 v[30:33], v[158:161], v[150:153], v[30:33]
	v_mfma_f32_16x16x32_bf16 v[26:29], v[182:185], v[150:153], v[26:29]
	v_mfma_f32_16x16x32_bf16 v[22:25], v[186:189], v[150:153], v[22:25]
	v_mfma_f32_16x16x32_bf16 v[18:21], v[206:209], v[150:153], v[18:21]
	v_mfma_f32_16x16x32_bf16 v[14:17], v[158:161], v[154:157], v[14:17]
	v_mfma_f32_16x16x32_bf16 v[10:13], v[182:185], v[154:157], v[10:13]
	v_mfma_f32_16x16x32_bf16 v[2:5], v[186:189], v[154:157], v[2:5]
	v_mfma_f32_16x16x32_bf16 v[6:9], v[206:209], v[154:157], v[6:9]
	s_waitcnt vmcnt(0) lgkmcnt(0)
	s_barrier
	v_mfma_f32_16x16x32_bf16 v[94:97], v[114:117], v[98:101], v[94:97]
	s_add_u32 m0, s8, 0x8000
	ds_read_b128 v[142:145], v138
	ds_read_b128 v[158:161], v137 offset:16384
	v_mfma_f32_16x16x32_bf16 v[90:93], v[118:121], v[98:101], v[90:93]
	global_load_lds_dwordx4 v50, s[0:1]
	v_mfma_f32_16x16x32_bf16 v[86:89], v[122:125], v[98:101], v[86:89]
	s_add_u32 m0, s8, 0x9000
	ds_read_b128 v[182:185], v137 offset:18432
	ds_read_b128 v[186:189], v137 offset:20480
	v_mfma_f32_16x16x32_bf16 v[74:77], v[126:129], v[98:101], v[74:77]
	global_load_lds_dwordx4 v51, s[0:1]
	v_mfma_f32_16x16x32_bf16 v[46:49], v[114:117], v[102:105], v[46:49]
	s_add_u32 m0, s8, 0xa000
	ds_read_b128 v[206:209], v137 offset:22528
	ds_read_b128 v[146:149], v138 offset:2048
	v_mfma_f32_16x16x32_bf16 v[42:45], v[118:121], v[102:105], v[42:45]
	global_load_lds_dwordx4 v52, s[0:1]
	v_mfma_f32_16x16x32_bf16 v[38:41], v[122:125], v[102:105], v[38:41]
	s_add_u32 m0, s8, 0xb000
	ds_read_b128 v[150:153], v138 offset:4096
	ds_read_b128 v[154:157], v138 offset:6144
	v_mfma_f32_16x16x32_bf16 v[34:37], v[126:129], v[102:105], v[34:37]
	global_load_lds_dwordx4 v53, s[0:1]
	v_mfma_f32_16x16x32_bf16 v[30:33], v[114:117], v[106:109], v[30:33]
	s_add_u32 m0, s8, 0xc000
	v_mfma_f32_16x16x32_bf16 v[26:29], v[118:121], v[106:109], v[26:29]
	global_load_lds_dwordx4 v54, s[4:5]
	v_mfma_f32_16x16x32_bf16 v[22:25], v[122:125], v[106:109], v[22:25]
	s_add_u32 m0, s8, 0xd000
	v_mfma_f32_16x16x32_bf16 v[18:21], v[126:129], v[106:109], v[18:21]
	global_load_lds_dwordx4 v55, s[4:5]
	v_mfma_f32_16x16x32_bf16 v[14:17], v[114:117], v[110:113], v[14:17]
	s_add_u32 m0, s8, 0xe000
	v_mfma_f32_16x16x32_bf16 v[10:13], v[118:121], v[110:113], v[10:13]
	global_load_lds_dwordx4 v56, s[4:5]
	v_mfma_f32_16x16x32_bf16 v[2:5], v[122:125], v[110:113], v[2:5]
	s_add_u32 m0, s8, 0xf000
	v_mfma_f32_16x16x32_bf16 v[6:9], v[126:129], v[110:113], v[6:9]
	global_load_lds_dwordx4 v57, s[4:5]
	s_add_u32 s0, s0, 0x80
	s_addc_u32 s1, s1, 0
	s_add_u32 s4, s4, 0x80
	s_addc_u32 s5, s5, 0
	s_waitcnt lgkmcnt(0)
	v_mfma_f32_16x16x32_bf16 v[94:97], v[158:161], v[142:145], v[94:97]
	ds_read_b128 v[98:101], v139
	ds_read_b128 v[114:117], v140 offset:16384
	v_mfma_f32_16x16x32_bf16 v[90:93], v[182:185], v[142:145], v[90:93]
	v_mfma_f32_16x16x32_bf16 v[86:89], v[186:189], v[142:145], v[86:89]
	ds_read_b128 v[118:121], v140 offset:18432
	ds_read_b128 v[122:125], v140 offset:20480
	v_mfma_f32_16x16x32_bf16 v[74:77], v[206:209], v[142:145], v[74:77]
	v_mfma_f32_16x16x32_bf16 v[46:49], v[158:161], v[146:149], v[46:49]
	ds_read_b128 v[126:129], v140 offset:22528
	ds_read_b128 v[102:105], v139 offset:2048
	v_mfma_f32_16x16x32_bf16 v[42:45], v[182:185], v[146:149], v[42:45]
	v_mfma_f32_16x16x32_bf16 v[38:41], v[186:189], v[146:149], v[38:41]
	ds_read_b128 v[106:109], v139 offset:4096
	ds_read_b128 v[110:113], v139 offset:6144
	v_mfma_f32_16x16x32_bf16 v[34:37], v[206:209], v[146:149], v[34:37]
	v_mfma_f32_16x16x32_bf16 v[30:33], v[158:161], v[150:153], v[30:33]
	v_mfma_f32_16x16x32_bf16 v[26:29], v[182:185], v[150:153], v[26:29]
	v_mfma_f32_16x16x32_bf16 v[22:25], v[186:189], v[150:153], v[22:25]
	v_mfma_f32_16x16x32_bf16 v[18:21], v[206:209], v[150:153], v[18:21]
	v_mfma_f32_16x16x32_bf16 v[14:17], v[158:161], v[154:157], v[14:17]
	v_mfma_f32_16x16x32_bf16 v[10:13], v[182:185], v[154:157], v[10:13]
	v_mfma_f32_16x16x32_bf16 v[2:5], v[186:189], v[154:157], v[2:5]
	v_mfma_f32_16x16x32_bf16 v[6:9], v[206:209], v[154:157], v[6:9]
	s_add_i32 s9, s9, -1
	s_waitcnt vmcnt(0) lgkmcnt(0)
	s_barrier
	s_cmp_lg_u32 s9, 0
	s_cbranch_scc1 .Lg1_loop
	v_mfma_f32_16x16x32_bf16 v[94:97], v[114:117], v[98:101], v[94:97]
	ds_read_b128 v[142:145], v138 offset:32768
	ds_read_b128 v[158:161], v137 offset:49152
	v_mfma_f32_16x16x32_bf16 v[90:93], v[118:121], v[98:101], v[90:93]
	v_mfma_f32_16x16x32_bf16 v[86:89], v[122:125], v[98:101], v[86:89]
	ds_read_b128 v[182:185], v137 offset:51200
	ds_read_b128 v[186:189], v137 offset:53248
	v_mfma_f32_16x16x32_bf16 v[74:77], v[126:129], v[98:101], v[74:77]
	v_mfma_f32_16x16x32_bf16 v[46:49], v[114:117], v[102:105], v[46:49]
	ds_read_b128 v[206:209], v137 offset:55296
	ds_read_b128 v[146:149], v138 offset:34816
	v_mfma_f32_16x16x32_bf16 v[42:45], v[118:121], v[102:105], v[42:45]
	v_mfma_f32_16x16x32_bf16 v[38:41], v[122:125], v[102:105], v[38:41]
	ds_read_b128 v[150:153], v138 offset:36864
	ds_read_b128 v[154:157], v138 offset:38912
	v_mfma_f32_16x16x32_bf16 v[34:37], v[126:129], v[102:105], v[34:37]
	v_mfma_f32_16x16x32_bf16 v[30:33], v[114:117], v[106:109], v[30:33]
	v_mfma_f32_16x16x32_bf16 v[26:29], v[118:121], v[106:109], v[26:29]
	v_mfma_f32_16x16x32_bf16 v[22:25], v[122:125], v[106:109], v[22:25]
	v_mfma_f32_16x16x32_bf16 v[18:21], v[126:129], v[106:109], v[18:21]
	v_mfma_f32_16x16x32_bf16 v[14:17], v[114:117], v[110:113], v[14:17]
	v_mfma_f32_16x16x32_bf16 v[10:13], v[118:121], v[110:113], v[10:13]
	v_mfma_f32_16x16x32_bf16 v[2:5], v[122:125], v[110:113], v[2:5]
	v_mfma_f32_16x16x32_bf16 v[6:9], v[126:129], v[110:113], v[6:9]
	s_waitcnt lgkmcnt(0)
	v_mfma_f32_16x16x32_bf16 v[94:97], v[158:161], v[142:145], v[94:97]
	ds_read_b128 v[98:101], v139 offset:32768
	ds_read_b128 v[114:117], v140 offset:49152
	v_mfma_f32_16x16x32_bf16 v[90:93], v[182:185], v[142:145], v[90:93]
	v_mfma_f32_16x16x32_bf16 v[86:89], v[186:189], v[142:145], v[86:89]
	ds_read_b128 v[118:121], v140 offset:51200
	ds_read_b128 v[122:125], v140 offset:53248
	v_mfma_f32_16x16x32_bf16 v[74:77], v[206:209], v[142:145], v[74:77]
	v_mfma_f32_16x16x32_bf16 v[46:49], v[158:161], v[146:149], v[46:49]
	ds_read_b128 v[126:129], v140 offset:55296
	ds_read_b128 v[102:105], v139 offset:34816
	v_mfma_f32_16x16x32_bf16 v[42:45], v[182:185], v[146:149], v[42:45]
	v_mfma_f32_16x16x32_bf16 v[38:41], v[186:189], v[146:149], v[38:41]
	ds_read_b128 v[106:109], v139 offset:36864
	ds_read_b128 v[110:113], v139 offset:38912
	v_mfma_f32_16x16x32_bf16 v[34:37], v[206:209], v[146:149], v[34:37]
	v_mfma_f32_16x16x32_bf16 v[30:33], v[158:161], v[150:153], v[30:33]
	v_mfma_f32_16x16x32_bf16 v[26:29], v[182:185], v[150:153], v[26:29]
	v_mfma_f32_16x16x32_bf16 v[22:25], v[186:189], v[150:153], v[22:25]
	v_mfma_f32_16x16x32_bf16 v[18:21], v[206:209], v[150:153], v[18:21]
	v_mfma_f32_16x16x32_bf16 v[14:17], v[158:161], v[154:157], v[14:17]
	v_mfma_f32_16x16x32_bf16 v[10:13], v[182:185], v[154:157], v[10:13]
	v_mfma_f32_16x16x32_bf16 v[2:5], v[186:189], v[154:157], v[2:5]
	v_mfma_f32_16x16x32_bf16 v[6:9], v[206:209], v[154:157], v[6:9]
	s_waitcnt lgkmcnt(0)
	s_barrier
	v_mfma_f32_16x16x32_bf16 v[94:97], v[114:117], v[98:101], v[94:97]
	v_mfma_f32_16x16x32_bf16 v[90:93], v[118:121], v[98:101], v[90:93]
	v_mfma_f32_16x16x32_bf16 v[86:89], v[122:125], v[98:101], v[86:89]
	v_mfma_f32_16x16x32_bf16 v[74:77], v[126:129], v[98:101], v[74:77]
	v_mfma_f32_16x16x32_bf16 v[46:49], v[114:117], v[102:105], v[46:49]
	v_mfma_f32_16x16x32_bf16 v[42:45], v[118:121], v[102:105], v[42:45]
	v_mfma_f32_16x16x32_bf16 v[38:41], v[122:125], v[102:105], v[38:41]
	v_mfma_f32_16x16x32_bf16 v[34:37], v[126:129], v[102:105], v[34:37]
	v_mfma_f32_16x16x32_bf16 v[30:33], v[114:117], v[106:109], v[30:33]
	v_mfma_f32_16x16x32_bf16 v[26:29], v[118:121], v[106:109], v[26:29]
	v_mfma_f32_16x16x32_bf16 v[22:25], v[122:125], v[106:109], v[22:25]
	v_mfma_f32_16x16x32_bf16 v[18:21], v[126:129], v[106:109], v[18:21]
	v_mfma_f32_16x16x32_bf16 v[14:17], v[114:117], v[110:113], v[14:17]
	v_mfma_f32_16x16x32_bf16 v[10:13], v[118:121], v[110:113], v[10:13]
	v_mfma_f32_16x16x32_bf16 v[2:5], v[122:125], v[110:113], v[2:5]
	v_mfma_f32_16x16x32_bf16 v[6:9], v[126:129], v[110:113], v[6:9]
	s_nop 7
	s_nop 2
